# v33 + non-temporal stores for the mlp-up output U
# baseline (speedup 1.0000x reference)
.LBB0_108:
	v_mov_b32_e32 v142, v144
	v_mov_b32_e32 v143, v145
	s_lshl_b32 s4, s22, 8
	s_add_i32 s4, s4, s40
	v_add_u32_e32 v142, s4, v142
	s_lshl_b32 s4, s47, 8
	s_or_b32 s4, s4, s41
	v_lshl_add_u32 v148, v143, 3, s4
	v_ashrrev_i32_e32 v143, 31, v142
	v_lshlrev_b64 v[142:143], 13, v[142:143]
	v_max_f32_e32 v124, 0, v124
	v_max_f32_e32 v125, 0, v125
	v_ashrrev_i32_e32 v149, 31, v148
	v_lshl_add_u64 v[142:143], s[10:11], 0, v[142:143]
	v_lshl_add_u64 v[142:143], v[148:149], 1, v[142:143]
	v_pk_mul_f32 v[148:149], v[124:125], v[124:125]
	v_max_f32_e32 v125, v126, v126
	v_max_f32_e32 v128, 0, v128
	v_max_f32_e32 v129, 0, v129
	v_max_f32_e32 v124, 0, v130
	v_max_f32_e32 v126, 0, v125
	v_max_f32_e32 v125, 0, v131
	v_max_f32_e32 v127, 0, v127
	v_pk_mul_f32 v[128:129], v[128:129], v[128:129]
	v_pk_mul_f32 v[130:131], v[124:125], v[124:125]
	v_pk_mul_f32 v[150:151], v[126:127], v[126:127]
	v_max_f32_e32 v116, 0, v116
	v_max_f32_e32 v117, 0, v117
	v_cvt_pk_bf16_f32 v124, v128, v129
	v_cvt_pk_bf16_f32 v125, v130, v131
	v_cvt_pk_bf16_f32 v126, v148, v149
	v_cvt_pk_bf16_f32 v127, v150, v151
	global_store_dwordx4 v[142:143], v[124:127], off nt
	v_max_f32_e32 v120, 0, v120
	v_max_f32_e32 v121, 0, v121
	v_pk_mul_f32 v[124:125], v[116:117], v[116:117]
	v_max_f32_e32 v117, v118, v118
	v_max_f32_e32 v116, 0, v122
	v_max_f32_e32 v118, 0, v117
	v_max_f32_e32 v117, 0, v123
	v_max_f32_e32 v119, 0, v119
	v_pk_mul_f32 v[120:121], v[120:121], v[120:121]
	v_pk_mul_f32 v[122:123], v[116:117], v[116:117]
	v_pk_mul_f32 v[126:127], v[118:119], v[118:119]
	v_max_f32_e32 v108, 0, v108
	v_max_f32_e32 v109, 0, v109
	v_cvt_pk_bf16_f32 v116, v120, v121
	v_cvt_pk_bf16_f32 v117, v122, v123
	v_cvt_pk_bf16_f32 v118, v124, v125
	v_cvt_pk_bf16_f32 v119, v126, v127
	global_store_dwordx4 v[142:143], v[116:119], off offset:256 nt
	v_max_f32_e32 v112, 0, v112
	v_max_f32_e32 v113, 0, v113
	v_pk_mul_f32 v[118:119], v[108:109], v[108:109]
	v_max_f32_e32 v109, v110, v110
	s_mov_b64 s[4:5], 0x20000
	v_max_f32_e32 v108, 0, v114
	v_max_f32_e32 v110, 0, v109
	v_max_f32_e32 v109, 0, v115
	v_max_f32_e32 v111, 0, v111
	v_lshl_add_u64 v[116:117], v[142:143], 0, s[4:5]
	v_pk_mul_f32 v[112:113], v[112:113], v[112:113]
	s_mov_b32 s4, 0x20000
	v_pk_mul_f32 v[114:115], v[108:109], v[108:109]
	v_pk_mul_f32 v[120:121], v[110:111], v[110:111]
	v_cvt_pk_bf16_f32 v108, v112, v113
	v_add_co_u32_e32 v112, vcc, s4, v142
	v_max_f32_e32 v100, 0, v100
	v_max_f32_e32 v101, 0, v101
	v_cvt_pk_bf16_f32 v109, v114, v115
	v_cvt_pk_bf16_f32 v110, v118, v119
	v_cvt_pk_bf16_f32 v111, v120, v121
	v_addc_co_u32_e32 v113, vcc, 0, v143, vcc
	global_store_dwordx4 v[112:113], v[108:111], off nt
	v_max_f32_e32 v104, 0, v104
	v_max_f32_e32 v105, 0, v105
	v_pk_mul_f32 v[108:109], v[100:101], v[100:101]
	v_max_f32_e32 v101, v102, v102
	v_max_f32_e32 v100, 0, v106
	v_max_f32_e32 v102, 0, v101
	v_max_f32_e32 v101, 0, v107
	v_max_f32_e32 v103, 0, v103
	v_pk_mul_f32 v[104:105], v[104:105], v[104:105]
	v_pk_mul_f32 v[106:107], v[100:101], v[100:101]
	v_pk_mul_f32 v[110:111], v[102:103], v[102:103]
	v_max_f32_e32 v92, 0, v92
	v_max_f32_e32 v93, 0, v93
	v_cvt_pk_bf16_f32 v100, v104, v105
	v_cvt_pk_bf16_f32 v101, v106, v107
	v_cvt_pk_bf16_f32 v102, v108, v109
	v_cvt_pk_bf16_f32 v103, v110, v111
	global_store_dwordx4 v[116:117], v[100:103], off offset:256 nt
	v_max_f32_e32 v96, 0, v96
	v_max_f32_e32 v97, 0, v97
	v_pk_mul_f32 v[102:103], v[92:93], v[92:93]
	v_max_f32_e32 v93, v94, v94
	s_mov_b64 s[4:5], 0x40000
	v_max_f32_e32 v92, 0, v98
	v_max_f32_e32 v94, 0, v93
	v_max_f32_e32 v93, 0, v99
	v_max_f32_e32 v95, 0, v95
	v_lshl_add_u64 v[100:101], v[142:143], 0, s[4:5]
	v_pk_mul_f32 v[96:97], v[96:97], v[96:97]
	s_mov_b32 s4, 0x40000
	v_pk_mul_f32 v[98:99], v[92:93], v[92:93]
	v_pk_mul_f32 v[104:105], v[94:95], v[94:95]
	v_cvt_pk_bf16_f32 v92, v96, v97
	v_add_co_u32_e32 v96, vcc, s4, v142
	v_max_f32_e32 v84, 0, v84
	v_max_f32_e32 v85, 0, v85
	v_cvt_pk_bf16_f32 v93, v98, v99
	v_cvt_pk_bf16_f32 v94, v102, v103
	v_cvt_pk_bf16_f32 v95, v104, v105
	v_addc_co_u32_e32 v97, vcc, 0, v143, vcc
	global_store_dwordx4 v[96:97], v[92:95], off nt
	v_max_f32_e32 v88, 0, v88
	v_max_f32_e32 v89, 0, v89
	v_pk_mul_f32 v[92:93], v[84:85], v[84:85]
	v_max_f32_e32 v85, v86, v86
	v_max_f32_e32 v84, 0, v90
	v_max_f32_e32 v86, 0, v85
	v_max_f32_e32 v85, 0, v91
	v_max_f32_e32 v87, 0, v87
	v_pk_mul_f32 v[88:89], v[88:89], v[88:89]
	v_pk_mul_f32 v[90:91], v[84:85], v[84:85]
	v_pk_mul_f32 v[94:95], v[86:87], v[86:87]
	v_max_f32_e32 v76, 0, v76
	v_max_f32_e32 v77, 0, v77
	v_cvt_pk_bf16_f32 v84, v88, v89
	v_cvt_pk_bf16_f32 v85, v90, v91
	v_cvt_pk_bf16_f32 v86, v92, v93
	v_cvt_pk_bf16_f32 v87, v94, v95
	global_store_dwordx4 v[100:101], v[84:87], off offset:256 nt
	v_max_f32_e32 v80, 0, v80
	v_max_f32_e32 v81, 0, v81
	v_pk_mul_f32 v[86:87], v[76:77], v[76:77]
	v_max_f32_e32 v77, v78, v78
	s_mov_b64 s[4:5], 0x60000
	v_max_f32_e32 v76, 0, v82
	v_max_f32_e32 v78, 0, v77
	v_max_f32_e32 v77, 0, v83
	v_max_f32_e32 v79, 0, v79
	v_lshl_add_u64 v[84:85], v[142:143], 0, s[4:5]
	v_pk_mul_f32 v[80:81], v[80:81], v[80:81]
	s_mov_b32 s4, 0x60000
	v_pk_mul_f32 v[82:83], v[76:77], v[76:77]
	v_pk_mul_f32 v[88:89], v[78:79], v[78:79]
	v_cvt_pk_bf16_f32 v76, v80, v81
	v_add_co_u32_e32 v80, vcc, s4, v142
	v_max_f32_e32 v68, 0, v68
	v_max_f32_e32 v69, 0, v69
	v_cvt_pk_bf16_f32 v77, v82, v83
	v_cvt_pk_bf16_f32 v78, v86, v87
	v_cvt_pk_bf16_f32 v79, v88, v89
	v_addc_co_u32_e32 v81, vcc, 0, v143, vcc
	global_store_dwordx4 v[80:81], v[76:79], off nt
	v_max_f32_e32 v72, 0, v72
	v_max_f32_e32 v73, 0, v73
	v_pk_mul_f32 v[76:77], v[68:69], v[68:69]
	v_max_f32_e32 v69, v70, v70
	v_max_f32_e32 v68, 0, v74
	v_max_f32_e32 v70, 0, v69
	v_max_f32_e32 v69, 0, v75
	v_max_f32_e32 v71, 0, v71
	v_pk_mul_f32 v[72:73], v[72:73], v[72:73]
	v_pk_mul_f32 v[74:75], v[68:69], v[68:69]
	v_pk_mul_f32 v[78:79], v[70:71], v[70:71]
	v_max_f32_e32 v60, 0, v60
	v_max_f32_e32 v61, 0, v61
	v_cvt_pk_bf16_f32 v68, v72, v73
	v_cvt_pk_bf16_f32 v69, v74, v75
	v_cvt_pk_bf16_f32 v70, v76, v77
	v_cvt_pk_bf16_f32 v71, v78, v79
	global_store_dwordx4 v[84:85], v[68:71], off offset:256 nt
	v_max_f32_e32 v64, 0, v64
	v_max_f32_e32 v65, 0, v65
	v_pk_mul_f32 v[70:71], v[60:61], v[60:61]
	v_max_f32_e32 v61, v62, v62
	s_mov_b64 s[4:5], 0x100000
	v_max_f32_e32 v60, 0, v66
	v_max_f32_e32 v62, 0, v61
	v_max_f32_e32 v61, 0, v67
	v_max_f32_e32 v63, 0, v63
	v_lshl_add_u64 v[68:69], v[142:143], 0, s[4:5]
	v_pk_mul_f32 v[64:65], v[64:65], v[64:65]
	s_mov_b32 s4, 0x100000
	v_pk_mul_f32 v[66:67], v[60:61], v[60:61]
	v_pk_mul_f32 v[72:73], v[62:63], v[62:63]
	v_cvt_pk_bf16_f32 v60, v64, v65
	v_add_co_u32_e32 v64, vcc, s4, v142
	v_max_f32_e32 v52, 0, v52
	v_max_f32_e32 v53, 0, v53
	v_cvt_pk_bf16_f32 v61, v66, v67
	v_cvt_pk_bf16_f32 v62, v70, v71
	v_cvt_pk_bf16_f32 v63, v72, v73
	v_addc_co_u32_e32 v65, vcc, 0, v143, vcc
	global_store_dwordx4 v[64:65], v[60:63], off nt
	v_max_f32_e32 v56, 0, v56
	v_max_f32_e32 v57, 0, v57
	v_pk_mul_f32 v[60:61], v[52:53], v[52:53]
	v_max_f32_e32 v53, v54, v54
	v_max_f32_e32 v52, 0, v58
	v_max_f32_e32 v54, 0, v53
	v_max_f32_e32 v53, 0, v59
	v_max_f32_e32 v55, 0, v55
	v_pk_mul_f32 v[56:57], v[56:57], v[56:57]
	v_pk_mul_f32 v[58:59], v[52:53], v[52:53]
	v_pk_mul_f32 v[62:63], v[54:55], v[54:55]
	v_max_f32_e32 v44, 0, v44
	v_max_f32_e32 v45, 0, v45
	v_cvt_pk_bf16_f32 v52, v56, v57
	v_cvt_pk_bf16_f32 v53, v58, v59
	v_cvt_pk_bf16_f32 v54, v60, v61
	v_cvt_pk_bf16_f32 v55, v62, v63
	global_store_dwordx4 v[68:69], v[52:55], off offset:256 nt
	v_max_f32_e32 v48, 0, v48
	v_max_f32_e32 v49, 0, v49
	v_pk_mul_f32 v[54:55], v[44:45], v[44:45]
	v_max_f32_e32 v45, v46, v46
	s_mov_b64 s[4:5], 0x120000
	v_max_f32_e32 v44, 0, v50
	v_max_f32_e32 v46, 0, v45
	v_max_f32_e32 v45, 0, v51
	v_max_f32_e32 v47, 0, v47
	v_lshl_add_u64 v[52:53], v[142:143], 0, s[4:5]
	v_pk_mul_f32 v[48:49], v[48:49], v[48:49]
	s_mov_b32 s4, 0x120000
	v_pk_mul_f32 v[50:51], v[44:45], v[44:45]
	v_pk_mul_f32 v[56:57], v[46:47], v[46:47]
	v_cvt_pk_bf16_f32 v44, v48, v49
	v_add_co_u32_e32 v48, vcc, s4, v142
	v_max_f32_e32 v36, 0, v36
	v_max_f32_e32 v37, 0, v37
	v_cvt_pk_bf16_f32 v45, v50, v51
	v_cvt_pk_bf16_f32 v46, v54, v55
	v_cvt_pk_bf16_f32 v47, v56, v57
	v_addc_co_u32_e32 v49, vcc, 0, v143, vcc
	global_store_dwordx4 v[48:49], v[44:47], off nt
	v_max_f32_e32 v40, 0, v40
	v_max_f32_e32 v41, 0, v41
	v_pk_mul_f32 v[44:45], v[36:37], v[36:37]
	v_max_f32_e32 v37, v38, v38
	v_max_f32_e32 v36, 0, v42
	v_max_f32_e32 v38, 0, v37
	v_max_f32_e32 v37, 0, v43
	v_max_f32_e32 v39, 0, v39
	v_pk_mul_f32 v[40:41], v[40:41], v[40:41]
	v_pk_mul_f32 v[42:43], v[36:37], v[36:37]
	v_pk_mul_f32 v[46:47], v[38:39], v[38:39]
	v_max_f32_e32 v28, 0, v28
	v_max_f32_e32 v29, 0, v29
	v_cvt_pk_bf16_f32 v36, v40, v41
	v_cvt_pk_bf16_f32 v37, v42, v43
	v_cvt_pk_bf16_f32 v38, v44, v45
	v_cvt_pk_bf16_f32 v39, v46, v47
	global_store_dwordx4 v[52:53], v[36:39], off offset:256 nt
	v_max_f32_e32 v32, 0, v32
	v_max_f32_e32 v33, 0, v33
	v_pk_mul_f32 v[38:39], v[28:29], v[28:29]
	v_max_f32_e32 v29, v30, v30
	s_mov_b64 s[4:5], 0x140000
	v_max_f32_e32 v28, 0, v34
	v_max_f32_e32 v30, 0, v29
	v_max_f32_e32 v29, 0, v35
	v_max_f32_e32 v31, 0, v31
	v_lshl_add_u64 v[36:37], v[142:143], 0, s[4:5]
	v_pk_mul_f32 v[32:33], v[32:33], v[32:33]
	s_mov_b32 s4, 0x140000
	v_pk_mul_f32 v[34:35], v[28:29], v[28:29]
	v_pk_mul_f32 v[40:41], v[30:31], v[30:31]
	v_cvt_pk_bf16_f32 v28, v32, v33
	v_add_co_u32_e32 v32, vcc, s4, v142
	v_max_f32_e32 v20, 0, v20
	v_max_f32_e32 v21, 0, v21
	v_cvt_pk_bf16_f32 v29, v34, v35
	v_cvt_pk_bf16_f32 v30, v38, v39
	v_cvt_pk_bf16_f32 v31, v40, v41
	v_addc_co_u32_e32 v33, vcc, 0, v143, vcc
	global_store_dwordx4 v[32:33], v[28:31], off nt
	v_max_f32_e32 v24, 0, v24
	v_max_f32_e32 v25, 0, v25
	v_pk_mul_f32 v[28:29], v[20:21], v[20:21]
	v_max_f32_e32 v21, v22, v22
	v_max_f32_e32 v20, 0, v26
	v_max_f32_e32 v22, 0, v21
	v_max_f32_e32 v21, 0, v27
	v_max_f32_e32 v23, 0, v23
	v_pk_mul_f32 v[24:25], v[24:25], v[24:25]
	v_pk_mul_f32 v[26:27], v[20:21], v[20:21]
	v_pk_mul_f32 v[30:31], v[22:23], v[22:23]
	v_max_f32_e32 v12, 0, v12
	v_max_f32_e32 v13, 0, v13
	v_cvt_pk_bf16_f32 v20, v24, v25
	v_cvt_pk_bf16_f32 v21, v26, v27
	v_cvt_pk_bf16_f32 v22, v28, v29
	v_cvt_pk_bf16_f32 v23, v30, v31
	global_store_dwordx4 v[36:37], v[20:23], off offset:256 nt
	v_max_f32_e32 v16, 0, v16
	v_max_f32_e32 v17, 0, v17
	v_pk_mul_f32 v[22:23], v[12:13], v[12:13]
	v_max_f32_e32 v13, v14, v14
	s_mov_b64 s[4:5], 0x160000
	v_max_f32_e32 v12, 0, v18
	v_max_f32_e32 v14, 0, v13
	v_max_f32_e32 v13, 0, v19
	v_max_f32_e32 v15, 0, v15
	v_lshl_add_u64 v[20:21], v[142:143], 0, s[4:5]
	v_pk_mul_f32 v[16:17], v[16:17], v[16:17]
	s_mov_b32 s4, 0x160000
	v_pk_mul_f32 v[18:19], v[12:13], v[12:13]
	v_pk_mul_f32 v[24:25], v[14:15], v[14:15]
	v_cvt_pk_bf16_f32 v12, v16, v17
	v_add_co_u32_e32 v16, vcc, s4, v142
	v_max_f32_e32 v4, 0, v4
	v_max_f32_e32 v5, 0, v5
	v_cvt_pk_bf16_f32 v13, v18, v19
	v_cvt_pk_bf16_f32 v14, v22, v23
	v_cvt_pk_bf16_f32 v15, v24, v25
	v_addc_co_u32_e32 v17, vcc, 0, v143, vcc
	global_store_dwordx4 v[16:17], v[12:15], off nt
	v_max_f32_e32 v8, 0, v8
	v_max_f32_e32 v9, 0, v9
	v_pk_mul_f32 v[12:13], v[4:5], v[4:5]
	v_max_f32_e32 v5, v6, v6
	v_max_f32_e32 v4, 0, v10
	v_max_f32_e32 v6, 0, v5
	v_max_f32_e32 v5, 0, v11
	v_max_f32_e32 v7, 0, v7
	v_pk_mul_f32 v[8:9], v[8:9], v[8:9]
	v_pk_mul_f32 v[10:11], v[4:5], v[4:5]
	v_pk_mul_f32 v[14:15], v[6:7], v[6:7]
	v_cvt_pk_bf16_f32 v4, v8, v9
	v_cvt_pk_bf16_f32 v5, v10, v11
	v_cvt_pk_bf16_f32 v6, v12, v13
	v_cvt_pk_bf16_f32 v7, v14, v15
	s_andn2_b64 vcc, exec, s[6:7]
	s_mov_b64 s[4:5], -1
	s_mov_b32 s54, 0xe10000
	s_movk_i32 s55, 0x1fff
	global_store_dwordx4 v[20:21], v[4:7], off offset:256 nt
	s_cbranch_vccnz .LBB0_101
	s_andn2_b64 vcc, exec, s[8:9]
	s_cbranch_vccnz .LBB0_100
	s_barrier
	s_branch .LBB0_100
